# HGRN scan: waves 4-7 stage everything into a double-buffered LDS image (one barrier per chunk), waves 0-3 compute only; adaLN prologue loop with 16 loads in flight
# speedup vs baseline: 1.0163x; 1.0075x over previous
; DI void prologue(const Params& p, char* shm) {
;     ...
;           const int col = cb * 512 + tx; const float* w = p.in[4] + ((size_t)Ly * D + ks * 64) * 6144 + col;
;           float a[9];
; #pragma unroll
;           for (int c = 0; c < 9; ++c) a[c] = 0.f;
;           for (int k = 0; k < 64; ++k) { const float wv = w[(size_t)k * 6144];
; #pragma unroll
;               for (int c = 0; c < 9; ++c) a[c] += cond[c * 64 + k] * wv; }
.LBB0_11:
	v_lshl_add_u64 v[18:19], v[14:15], 0, s[8:9]
	v_add_co_u32_e32 v20, vcc, s10, v18
	global_load_dword v80, v[18:19], off
	s_nop 0
	v_addc_co_u32_e32 v21, vcc, 0, v19, vcc
	v_add_co_u32_e32 v22, vcc, s11, v18
	s_nop 0
	s_nop 0
	v_addc_co_u32_e32 v23, vcc, 0, v19, vcc
	v_add_co_u32_e32 v18, vcc, s12, v18
	s_add_u32 s8, s8, 0x18000
	s_addc_u32 s9, s9, 0
	s_nop 0
	v_addc_co_u32_e32 v19, vcc, 0, v19, vcc
	global_load_dword v82, v[20:21], off
	global_load_dword v84, v[22:23], off
	global_load_dword v86, v[18:19], off
	v_lshl_add_u64 v[18:19], v[14:15], 0, s[8:9]
	v_add_co_u32_e32 v20, vcc, s10, v18
	global_load_dword v88, v[18:19], off
	s_nop 0
	v_addc_co_u32_e32 v21, vcc, 0, v19, vcc
	v_add_co_u32_e32 v22, vcc, s11, v18
	s_nop 0
	s_nop 0
	v_addc_co_u32_e32 v23, vcc, 0, v19, vcc
	v_add_co_u32_e32 v18, vcc, s12, v18
	s_add_u32 s8, s8, 0x18000
	s_addc_u32 s9, s9, 0
	s_nop 0
	v_addc_co_u32_e32 v19, vcc, 0, v19, vcc
	global_load_dword v90, v[20:21], off
	global_load_dword v92, v[22:23], off
	global_load_dword v94, v[18:19], off
	v_lshl_add_u64 v[18:19], v[14:15], 0, s[8:9]
	v_add_co_u32_e32 v20, vcc, s10, v18
	global_load_dword v96, v[18:19], off
	s_nop 0
	v_addc_co_u32_e32 v21, vcc, 0, v19, vcc
	v_add_co_u32_e32 v22, vcc, s11, v18
	s_nop 0
	s_nop 0
	v_addc_co_u32_e32 v23, vcc, 0, v19, vcc
	v_add_co_u32_e32 v18, vcc, s12, v18
	s_add_u32 s8, s8, 0x18000
	s_addc_u32 s9, s9, 0
	s_nop 0
	v_addc_co_u32_e32 v19, vcc, 0, v19, vcc
	global_load_dword v98, v[20:21], off
	global_load_dword v100, v[22:23], off
	global_load_dword v102, v[18:19], off
	v_lshl_add_u64 v[18:19], v[14:15], 0, s[8:9]
	v_add_co_u32_e32 v20, vcc, s10, v18
	global_load_dword v104, v[18:19], off
	s_nop 0
	v_addc_co_u32_e32 v21, vcc, 0, v19, vcc
	v_add_co_u32_e32 v22, vcc, s11, v18
	s_nop 0
	s_nop 0
	v_addc_co_u32_e32 v23, vcc, 0, v19, vcc
	v_add_co_u32_e32 v18, vcc, s12, v18
	s_add_u32 s8, s8, 0x18000
	s_addc_u32 s9, s9, 0
	s_nop 0
	v_addc_co_u32_e32 v19, vcc, 0, v19, vcc
	global_load_dword v106, v[20:21], off
	global_load_dword v108, v[22:23], off
	global_load_dword v110, v[18:19], off
	v_mov_b32_e32 v50, s5
	ds_read_b128 v[18:21], v50
	ds_read_b128 v[22:25], v50 offset:256
	ds_read_b128 v[26:29], v50 offset:512
	ds_read_b128 v[30:33], v50 offset:768
	ds_read_b128 v[34:37], v50 offset:1024
	ds_read_b128 v[38:41], v50 offset:1280
	ds_read_b128 v[42:45], v50 offset:1536
	ds_read_b128 v[46:49], v50 offset:1792
	ds_read_b128 v[50:53], v50 offset:2048
	s_waitcnt lgkmcnt(8)
	v_mov_b32_e32 v62, v18
	s_waitcnt lgkmcnt(7)
	v_mov_b32_e32 v63, v22
	v_mov_b32_e32 v22, v19
	v_mov_b32_e32 v18, v20
	v_mov_b32_e32 v19, v24
	v_mov_b32_e32 v24, v21
	s_waitcnt lgkmcnt(6)
	v_mov_b32_e32 v20, v26
	s_waitcnt lgkmcnt(5)
	v_mov_b32_e32 v21, v30
	v_mov_b32_e32 v30, v27
	v_mov_b32_e32 v26, v28
	v_mov_b32_e32 v27, v32
	v_mov_b32_e32 v32, v29
	s_waitcnt lgkmcnt(4)
	v_mov_b32_e32 v28, v34
	s_waitcnt lgkmcnt(3)
	v_mov_b32_e32 v29, v38
	v_mov_b32_e32 v38, v35
	v_mov_b32_e32 v34, v36
	v_mov_b32_e32 v35, v40
	v_mov_b32_e32 v40, v37
	s_waitcnt lgkmcnt(2)
	v_mov_b32_e32 v36, v42
	s_waitcnt lgkmcnt(1)
	v_mov_b32_e32 v37, v46
	v_mov_b32_e32 v46, v43
	v_mov_b32_e32 v42, v44
	v_mov_b32_e32 v43, v48
	s_add_i32 s5, s5, 16
	v_mov_b32_e32 v48, v45
	s_waitcnt vmcnt(15)
	v_pk_fma_f32 v[10:11], v[80:81], v[62:63], v[10:11] op_sel_hi:[0,1,1]
	v_pk_fma_f32 v[8:9], v[80:81], v[20:21], v[8:9] op_sel_hi:[0,1,1]
	v_pk_fma_f32 v[6:7], v[80:81], v[28:29], v[6:7] op_sel_hi:[0,1,1]
	v_pk_fma_f32 v[2:3], v[80:81], v[36:37], v[2:3] op_sel_hi:[0,1,1]
	s_waitcnt lgkmcnt(0)
	v_fmac_f32_e32 v17, v80, v50
	s_waitcnt vmcnt(14)
	v_pk_fma_f32 v[10:11], v[82:83], v[22:23], v[10:11] op_sel_hi:[0,1,1]
	v_pk_fma_f32 v[8:9], v[82:83], v[30:31], v[8:9] op_sel_hi:[0,1,1]
	v_pk_fma_f32 v[6:7], v[82:83], v[38:39], v[6:7] op_sel_hi:[0,1,1]
	v_pk_fma_f32 v[2:3], v[82:83], v[46:47], v[2:3] op_sel_hi:[0,1,1]
	v_fmac_f32_e32 v17, v82, v51
	s_waitcnt vmcnt(13)
	v_pk_fma_f32 v[10:11], v[84:85], v[18:19], v[10:11] op_sel_hi:[0,1,1]
	v_pk_fma_f32 v[8:9], v[84:85], v[26:27], v[8:9] op_sel_hi:[0,1,1]
	v_pk_fma_f32 v[6:7], v[84:85], v[34:35], v[6:7] op_sel_hi:[0,1,1]
	v_pk_fma_f32 v[2:3], v[84:85], v[42:43], v[2:3] op_sel_hi:[0,1,1]
	v_fmac_f32_e32 v17, v84, v52
	s_waitcnt vmcnt(12)
	v_pk_fma_f32 v[10:11], v[86:87], v[24:25], v[10:11] op_sel_hi:[0,1,1]
	v_pk_fma_f32 v[8:9], v[86:87], v[32:33], v[8:9] op_sel_hi:[0,1,1]
	v_pk_fma_f32 v[6:7], v[86:87], v[40:41], v[6:7] op_sel_hi:[0,1,1]
	v_pk_fma_f32 v[2:3], v[86:87], v[48:49], v[2:3] op_sel_hi:[0,1,1]
	v_fmac_f32_e32 v17, v86, v53
	v_mov_b32_e32 v50, s5
	ds_read_b128 v[18:21], v50
	ds_read_b128 v[22:25], v50 offset:256
	ds_read_b128 v[26:29], v50 offset:512
	ds_read_b128 v[30:33], v50 offset:768
	ds_read_b128 v[34:37], v50 offset:1024
	ds_read_b128 v[38:41], v50 offset:1280
	ds_read_b128 v[42:45], v50 offset:1536
	ds_read_b128 v[46:49], v50 offset:1792
	ds_read_b128 v[50:53], v50 offset:2048
	s_waitcnt lgkmcnt(8)
	v_mov_b32_e32 v62, v18
	s_waitcnt lgkmcnt(7)
	v_mov_b32_e32 v63, v22
	v_mov_b32_e32 v22, v19
	v_mov_b32_e32 v18, v20
	v_mov_b32_e32 v19, v24
	v_mov_b32_e32 v24, v21
	s_waitcnt lgkmcnt(6)
	v_mov_b32_e32 v20, v26
	s_waitcnt lgkmcnt(5)
	v_mov_b32_e32 v21, v30
	v_mov_b32_e32 v30, v27
	v_mov_b32_e32 v26, v28
	v_mov_b32_e32 v27, v32
	v_mov_b32_e32 v32, v29
	s_waitcnt lgkmcnt(4)
	v_mov_b32_e32 v28, v34
	s_waitcnt lgkmcnt(3)
	v_mov_b32_e32 v29, v38
	v_mov_b32_e32 v38, v35
	v_mov_b32_e32 v34, v36
	v_mov_b32_e32 v35, v40
	v_mov_b32_e32 v40, v37
	s_waitcnt lgkmcnt(2)
	v_mov_b32_e32 v36, v42
	s_waitcnt lgkmcnt(1)
	v_mov_b32_e32 v37, v46
	v_mov_b32_e32 v46, v43
	v_mov_b32_e32 v42, v44
	v_mov_b32_e32 v43, v48
	s_add_i32 s5, s5, 16
	v_mov_b32_e32 v48, v45
	s_waitcnt vmcnt(11)
; DI void prologue(const Params& p, char* shm) {
;     ...
;           for (int k = 0; k < 64; ++k) { const float wv = w[(size_t)k * 6144];
; #pragma unroll
;               for (int c = 0; c < 9; ++c) a[c] += cond[c * 64 + k] * wv; }
	v_pk_fma_f32 v[10:11], v[88:89], v[62:63], v[10:11] op_sel_hi:[0,1,1]
	v_pk_fma_f32 v[8:9], v[88:89], v[20:21], v[8:9] op_sel_hi:[0,1,1]
	v_pk_fma_f32 v[6:7], v[88:89], v[28:29], v[6:7] op_sel_hi:[0,1,1]
	v_pk_fma_f32 v[2:3], v[88:89], v[36:37], v[2:3] op_sel_hi:[0,1,1]
	s_waitcnt lgkmcnt(0)
	v_fmac_f32_e32 v17, v88, v50
	s_waitcnt vmcnt(10)
	v_pk_fma_f32 v[10:11], v[90:91], v[22:23], v[10:11] op_sel_hi:[0,1,1]
	v_pk_fma_f32 v[8:9], v[90:91], v[30:31], v[8:9] op_sel_hi:[0,1,1]
	v_pk_fma_f32 v[6:7], v[90:91], v[38:39], v[6:7] op_sel_hi:[0,1,1]
	v_pk_fma_f32 v[2:3], v[90:91], v[46:47], v[2:3] op_sel_hi:[0,1,1]
	v_fmac_f32_e32 v17, v90, v51
	s_waitcnt vmcnt(9)
	v_pk_fma_f32 v[10:11], v[92:93], v[18:19], v[10:11] op_sel_hi:[0,1,1]
	v_pk_fma_f32 v[8:9], v[92:93], v[26:27], v[8:9] op_sel_hi:[0,1,1]
	v_pk_fma_f32 v[6:7], v[92:93], v[34:35], v[6:7] op_sel_hi:[0,1,1]
	v_pk_fma_f32 v[2:3], v[92:93], v[42:43], v[2:3] op_sel_hi:[0,1,1]
	v_fmac_f32_e32 v17, v92, v52
	s_waitcnt vmcnt(8)
	v_pk_fma_f32 v[10:11], v[94:95], v[24:25], v[10:11] op_sel_hi:[0,1,1]
	v_pk_fma_f32 v[8:9], v[94:95], v[32:33], v[8:9] op_sel_hi:[0,1,1]
	v_pk_fma_f32 v[6:7], v[94:95], v[40:41], v[6:7] op_sel_hi:[0,1,1]
	v_pk_fma_f32 v[2:3], v[94:95], v[48:49], v[2:3] op_sel_hi:[0,1,1]
	v_fmac_f32_e32 v17, v94, v53
	v_mov_b32_e32 v50, s5
	ds_read_b128 v[18:21], v50
	ds_read_b128 v[22:25], v50 offset:256
	ds_read_b128 v[26:29], v50 offset:512
	ds_read_b128 v[30:33], v50 offset:768
	ds_read_b128 v[34:37], v50 offset:1024
	ds_read_b128 v[38:41], v50 offset:1280
	ds_read_b128 v[42:45], v50 offset:1536
	ds_read_b128 v[46:49], v50 offset:1792
	ds_read_b128 v[50:53], v50 offset:2048
	s_waitcnt lgkmcnt(8)
	v_mov_b32_e32 v62, v18
	s_waitcnt lgkmcnt(7)
	v_mov_b32_e32 v63, v22
	v_mov_b32_e32 v22, v19
	v_mov_b32_e32 v18, v20
	v_mov_b32_e32 v19, v24
	v_mov_b32_e32 v24, v21
	s_waitcnt lgkmcnt(6)
	v_mov_b32_e32 v20, v26
	s_waitcnt lgkmcnt(5)
	v_mov_b32_e32 v21, v30
	v_mov_b32_e32 v30, v27
	v_mov_b32_e32 v26, v28
	v_mov_b32_e32 v27, v32
	v_mov_b32_e32 v32, v29
	s_waitcnt lgkmcnt(4)
	v_mov_b32_e32 v28, v34
	s_waitcnt lgkmcnt(3)
	v_mov_b32_e32 v29, v38
	v_mov_b32_e32 v38, v35
	v_mov_b32_e32 v34, v36
	v_mov_b32_e32 v35, v40
	v_mov_b32_e32 v40, v37
	s_waitcnt lgkmcnt(2)
	v_mov_b32_e32 v36, v42
	s_waitcnt lgkmcnt(1)
	v_mov_b32_e32 v37, v46
	v_mov_b32_e32 v46, v43
	v_mov_b32_e32 v42, v44
	v_mov_b32_e32 v43, v48
	s_add_i32 s5, s5, 16
	v_mov_b32_e32 v48, v45
	s_waitcnt vmcnt(7)
	v_pk_fma_f32 v[10:11], v[96:97], v[62:63], v[10:11] op_sel_hi:[0,1,1]
	v_pk_fma_f32 v[8:9], v[96:97], v[20:21], v[8:9] op_sel_hi:[0,1,1]
	v_pk_fma_f32 v[6:7], v[96:97], v[28:29], v[6:7] op_sel_hi:[0,1,1]
	v_pk_fma_f32 v[2:3], v[96:97], v[36:37], v[2:3] op_sel_hi:[0,1,1]
	s_waitcnt lgkmcnt(0)
	v_fmac_f32_e32 v17, v96, v50
	s_waitcnt vmcnt(6)
	v_pk_fma_f32 v[10:11], v[98:99], v[22:23], v[10:11] op_sel_hi:[0,1,1]
	v_pk_fma_f32 v[8:9], v[98:99], v[30:31], v[8:9] op_sel_hi:[0,1,1]
	v_pk_fma_f32 v[6:7], v[98:99], v[38:39], v[6:7] op_sel_hi:[0,1,1]
	v_pk_fma_f32 v[2:3], v[98:99], v[46:47], v[2:3] op_sel_hi:[0,1,1]
	v_fmac_f32_e32 v17, v98, v51
	s_waitcnt vmcnt(5)
	v_pk_fma_f32 v[10:11], v[100:101], v[18:19], v[10:11] op_sel_hi:[0,1,1]
	v_pk_fma_f32 v[8:9], v[100:101], v[26:27], v[8:9] op_sel_hi:[0,1,1]
	v_pk_fma_f32 v[6:7], v[100:101], v[34:35], v[6:7] op_sel_hi:[0,1,1]
	v_pk_fma_f32 v[2:3], v[100:101], v[42:43], v[2:3] op_sel_hi:[0,1,1]
	v_fmac_f32_e32 v17, v100, v52
	s_waitcnt vmcnt(4)
	v_pk_fma_f32 v[10:11], v[102:103], v[24:25], v[10:11] op_sel_hi:[0,1,1]
	v_pk_fma_f32 v[8:9], v[102:103], v[32:33], v[8:9] op_sel_hi:[0,1,1]
	v_pk_fma_f32 v[6:7], v[102:103], v[40:41], v[6:7] op_sel_hi:[0,1,1]
	v_pk_fma_f32 v[2:3], v[102:103], v[48:49], v[2:3] op_sel_hi:[0,1,1]
	v_fmac_f32_e32 v17, v102, v53
	v_mov_b32_e32 v50, s5
	ds_read_b128 v[18:21], v50
	ds_read_b128 v[22:25], v50 offset:256
	ds_read_b128 v[26:29], v50 offset:512
	ds_read_b128 v[30:33], v50 offset:768
	ds_read_b128 v[34:37], v50 offset:1024
	ds_read_b128 v[38:41], v50 offset:1280
	ds_read_b128 v[42:45], v50 offset:1536
	ds_read_b128 v[46:49], v50 offset:1792
	ds_read_b128 v[50:53], v50 offset:2048
	s_waitcnt lgkmcnt(8)
	v_mov_b32_e32 v62, v18
	s_waitcnt lgkmcnt(7)
	v_mov_b32_e32 v63, v22
	v_mov_b32_e32 v22, v19
	v_mov_b32_e32 v18, v20
	v_mov_b32_e32 v19, v24
	v_mov_b32_e32 v24, v21
	s_waitcnt lgkmcnt(6)
	v_mov_b32_e32 v20, v26
	s_waitcnt lgkmcnt(5)
	v_mov_b32_e32 v21, v30
	v_mov_b32_e32 v30, v27
	v_mov_b32_e32 v26, v28
	v_mov_b32_e32 v27, v32
	v_mov_b32_e32 v32, v29
	s_waitcnt lgkmcnt(4)
	v_mov_b32_e32 v28, v34
	s_waitcnt lgkmcnt(3)
	v_mov_b32_e32 v29, v38
	v_mov_b32_e32 v38, v35
	v_mov_b32_e32 v34, v36
	v_mov_b32_e32 v35, v40
	v_mov_b32_e32 v40, v37
	s_waitcnt lgkmcnt(2)
	v_mov_b32_e32 v36, v42
	s_waitcnt lgkmcnt(1)
	v_mov_b32_e32 v37, v46
	v_mov_b32_e32 v46, v43
	v_mov_b32_e32 v42, v44
	v_mov_b32_e32 v43, v48
	s_add_i32 s5, s5, 16
	v_mov_b32_e32 v48, v45
	s_waitcnt vmcnt(3)
	v_pk_fma_f32 v[10:11], v[104:105], v[62:63], v[10:11] op_sel_hi:[0,1,1]
	v_pk_fma_f32 v[8:9], v[104:105], v[20:21], v[8:9] op_sel_hi:[0,1,1]
	v_pk_fma_f32 v[6:7], v[104:105], v[28:29], v[6:7] op_sel_hi:[0,1,1]
	v_pk_fma_f32 v[2:3], v[104:105], v[36:37], v[2:3] op_sel_hi:[0,1,1]
	s_waitcnt lgkmcnt(0)
	v_fmac_f32_e32 v17, v104, v50
	s_waitcnt vmcnt(2)
	v_pk_fma_f32 v[10:11], v[106:107], v[22:23], v[10:11] op_sel_hi:[0,1,1]
	v_pk_fma_f32 v[8:9], v[106:107], v[30:31], v[8:9] op_sel_hi:[0,1,1]
	v_pk_fma_f32 v[6:7], v[106:107], v[38:39], v[6:7] op_sel_hi:[0,1,1]
	v_pk_fma_f32 v[2:3], v[106:107], v[46:47], v[2:3] op_sel_hi:[0,1,1]
	v_fmac_f32_e32 v17, v106, v51
	s_waitcnt vmcnt(1)
	v_pk_fma_f32 v[10:11], v[108:109], v[18:19], v[10:11] op_sel_hi:[0,1,1]
	v_pk_fma_f32 v[8:9], v[108:109], v[26:27], v[8:9] op_sel_hi:[0,1,1]
	v_pk_fma_f32 v[6:7], v[108:109], v[34:35], v[6:7] op_sel_hi:[0,1,1]
	v_pk_fma_f32 v[2:3], v[108:109], v[42:43], v[2:3] op_sel_hi:[0,1,1]
	v_fmac_f32_e32 v17, v108, v52
	s_waitcnt vmcnt(0)
	v_pk_fma_f32 v[10:11], v[110:111], v[24:25], v[10:11] op_sel_hi:[0,1,1]
	v_pk_fma_f32 v[8:9], v[110:111], v[32:33], v[8:9] op_sel_hi:[0,1,1]
	v_pk_fma_f32 v[6:7], v[110:111], v[40:41], v[6:7] op_sel_hi:[0,1,1]
	v_pk_fma_f32 v[2:3], v[110:111], v[48:49], v[2:3] op_sel_hi:[0,1,1]
	v_fmac_f32_e32 v17, v110, v53
	s_cmp_eq_u32 s8, 0x180000
	s_cbranch_scc0 .LBB0_11
; DI void prologue(const Params& p, char* shm) {
;     ...
;       for (int it = bx; it < 4 * 16 * 12; it += gridDim.x) {
;     ...
;           for (int c = 0; c < 9; ++c) part[(((size_t)ks * 4 + Ly) * 9 + c) * 6144 + col] = a[c];
;       }
	s_ashr_i32 s5, s4, 31
	s_lshl_b64 s[4:5], s[4:5], 2
	s_add_u32 s4, s4, s6
	s_addc_u32 s6, s5, s7
	v_lshl_add_u64 v[4:5], v[4:5], 2, s[96:97]
	v_mad_u64_u32 v[4:5], s[4:5], s4, v16, v[4:5]
	s_mul_i32 s6, s6, 0x36000
	v_add_u32_e32 v5, s6, v5
	v_add_co_u32_e32 v14, vcc, s10, v4
	global_store_dword v[4:5], v10, off
	s_nop 0
	v_addc_co_u32_e32 v15, vcc, 0, v5, vcc
	v_add_co_u32_e32 v10, vcc, s11, v4
	global_store_dword v[14:15], v11, off
	s_nop 0
	v_addc_co_u32_e32 v11, vcc, 0, v5, vcc
	global_store_dword v[10:11], v8, off
	v_add_co_u32_e32 v10, vcc, s12, v4
	s_add_i32 s16, s16, s70
	s_nop 0
	v_addc_co_u32_e32 v11, vcc, 0, v5, vcc
	v_add_co_u32_e32 v8, vcc, s13, v4
	global_store_dword v[10:11], v9, off
	s_nop 0
	v_addc_co_u32_e32 v9, vcc, 0, v5, vcc
	global_store_dword v[8:9], v6, off
	v_add_co_u32_e32 v8, vcc, s14, v4
	s_cmpk_gt_i32 s16, 0x2ff
	s_nop 0
	v_addc_co_u32_e32 v9, vcc, 0, v5, vcc
	v_add_co_u32_e32 v6, vcc, s15, v4
	global_store_dword v[8:9], v7, off
	s_nop 0
	v_addc_co_u32_e32 v7, vcc, 0, v5, vcc
	global_store_dword v[6:7], v2, off
	v_add_co_u32_e32 v6, vcc, 0x2a000, v4
	s_nop 1
	v_addc_co_u32_e32 v7, vcc, 0, v5, vcc
	v_add_co_u32_e32 v2, vcc, 0x30000, v4
	global_store_dword v[6:7], v3, off
	s_nop 0
	v_addc_co_u32_e32 v3, vcc, 0, v5, vcc
	global_store_dword v[2:3], v17, off
	s_cbranch_scc0 .LBB0_7

; DI void hgrn_scan_mfma(const Params& p, char* shm) {
;     ...
;     for (int u = bx; u < 128; u += gridDim.x) {
;         const int dir = u & 1, head = (u >> 1) & 7, b = u >> 4;
;         const unsigned char* Fb = P + (dir ? P_HF1 : P_HF0); bf16_t* Oo = dir ? (bf16_t*)(p.ws + WS_P + P_HOB) : (bf16_t*)(p.ws + WS_H);
;         f32x4 S[8];
; #pragma unroll
;         for (int kt = 0; kt < 8; ++kt) S[kt] = (f32x4){0.f, 0.f, 0.f, 0.f};
;         const int lt = tid >> 4, lp = tid & 15;
;         u32x4 ra0, ra1, ra2, ra3, ra4, rb0, rb1, rb2, rb3, rb4;
;     ...
;         HG_LOAD(0, ra0, ra1, ra2, ra3, ra4); HG_LOAD(1, rb0, rb1, rb2, rb3, rb4);
;         for (int ch2 = 0; ch2 < LT / C; ch2 += 2) {
; #pragma unroll
;           for (int hh = 0; hh < 2; ++hh) {
;             const int ch = ch2 + hh;
;             if (hh == 0) HG_STAGE(ch, ra0, ra1, ra2, ra3, ra4); else HG_STAGE(ch, rb0, rb1, rb2, rb3, rb4);
;             { const bf16_t* kt16 = (const bf16_t*)KtL; const bf16_t* v16 = (const bf16_t*)VL; const int vcol = w * 16 + l15;
;     ...
;               const bf16x8 vf = __builtin_bit_cast(bf16x8, (u32x4){HG_U2(v16, g * 4 + 0, g * 4 + 1, vcol), HG_U2(v16, g * 4 + 2, g * 4 + 3, vcol), HG_U2(v16, 16 + g * 4 + 0, 16 + g * 4 + 1, vcol), HG_U2(v16, 16 + g * 4 + 2, 16 + g * 4 + 3, vcol)});
;               f32x4 sc00 = (f32x4){0.f, 0.f, 0.f, 0.f}, sc01 = sc00, sc11 = sc00, o0 = sc00, o1 = sc00;
; #pragma unroll
;               for (int kc = 0; kc < 4; ++kc) {
;                   const bf16x8 aK0 = *(const bf16x8*)(KtL + l15 * QS + kc * 64 + g * 16), aK1 = *(const bf16x8*)(KtL + (16 + l15) * QS + kc * 64 + g * 16);
;                   const bf16x8 bQ0 = *(const bf16x8*)(QtL + l15 * QS + kc * 64 + g * 16), bQ1 = *(const bf16x8*)(QtL + (16 + l15) * QS + kc * 64 + g * 16);
;                   sc00 = __builtin_amdgcn_mfma_f32_16x16x32_bf16(aK0, bQ0, sc00, 0, 0, 0);
;                   sc01 = __builtin_amdgcn_mfma_f32_16x16x32_bf16(aK0, bQ1, sc01, 0, 0, 0);
;                   sc11 = __builtin_amdgcn_mfma_f32_16x16x32_bf16(aK1, bQ1, sc11, 0, 0, 0);
;                   const int kp = kc;
;                   const u32x2 qa0 = *(const u32x2*)(QtL + l15 * QS + ((2 * kp) * 16 + g * 4) * 2), qb0 = *(const u32x2*)(QtL + l15 * QS + ((2 * kp + 1) * 16 + g * 4) * 2);
.LBB0_2416:
	s_or_b64 exec, exec, s[14:15]
	v_cndmask_b32_e64 v3, 0, 1, s[40:41]
	v_lshl_add_u64 v[142:143], s[0:1], 0, v[0:1]
	v_readfirstlane_b32 s14, v3
	s_lshl_b32 s55, s14, 3
	s_lshl_b32 s14, s31, 2
	s_and_b32 s56, s14, 0xe00
	s_and_b64 s[14:15], s[12:13], exec
	s_cselect_b32 s14, s72, 0x146da000
	s_add_u32 s14, s68, s14
	s_addc_u32 s15, s69, 0
	s_add_u32 s14, s14, s38
	s_addc_u32 s15, s15, 0
	v_lshl_add_u64 v[132:133], v[120:121], 1, s[14:15]
	s_and_b64 s[14:15], s[12:13], exec
	s_cselect_b32 s15, 0, -1
	s_cselect_b32 s14, s73, 0xfffffc00
	s_add_i32 s0, s54, s55
	s_mul_hi_i32 s1, s0, 0x48000
	s_mul_i32 s0, s0, 0x48000
	s_or_b32 s0, s0, s56
	v_mov_b32_e32 v44, 0
	s_mov_b32 s74, 0
	v_lshl_add_u64 v[128:129], v[116:117], 0, s[38:39]
	v_lshl_add_u64 v[130:131], v[118:119], 0, s[38:39]
	v_mul_hi_i32_i24_e32 v135, s14, v147
	v_mul_i32_i24_e32 v134, s14, v147
	s_lshl_b64 s[52:53], s[14:15], 5
	v_mul_hi_i32_i24_e32 v137, s14, v152
	v_mul_i32_i24_e32 v136, s14, v152
	v_mul_hi_i32_i24_e32 v139, s14, v153
	v_mul_i32_i24_e32 v138, s14, v153
	v_mul_hi_i32_i24_e32 v141, s14, v154
	v_mul_i32_i24_e32 v140, s14, v154
	v_lshl_add_u64 v[144:145], v[122:123], 0, s[0:1]
	s_movk_i32 s38, 0xffe0
	s_mov_b32 s76, 0
	v_mov_b32_e32 v45, v44
	v_mov_b32_e32 v46, v44
	v_mov_b32_e32 v47, v44
	v_mov_b32_e32 v48, v44
	v_mov_b32_e32 v49, v44
	v_mov_b32_e32 v50, v44
	v_mov_b32_e32 v51, v44
	v_mov_b32_e32 v52, v44
	v_mov_b32_e32 v53, v44
	v_mov_b32_e32 v54, v44
	v_mov_b32_e32 v55, v44
	v_mov_b32_e32 v56, v44
	v_mov_b32_e32 v57, v44
	v_mov_b32_e32 v58, v44
	v_mov_b32_e32 v59, v44
	v_mov_b32_e32 v60, v44
	v_mov_b32_e32 v61, v44
	v_mov_b32_e32 v62, v44
	v_mov_b32_e32 v63, v44
	v_mov_b32_e32 v64, v44
	v_mov_b32_e32 v65, v44
	v_mov_b32_e32 v66, v44
	v_mov_b32_e32 v67, v44
	v_mov_b32_e32 v72, v44
	v_mov_b32_e32 v73, v44
	v_mov_b32_e32 v74, v44
	v_mov_b32_e32 v75, v44
	v_mov_b32_e32 v68, v44
	v_mov_b32_e32 v69, v44
	v_mov_b32_e32 v70, v44
	v_mov_b32_e32 v71, v44
	s_cmp_lg_u32 s100, 0
	s_cbranch_scc1 .Lscanh_pro
	v_add_u32_e32 v195, 0x8000, v161
	v_add_u32_e32 v197, 0x9000, v161
.LBB0_2417:
	s_nop 0
	s_barrier
	s_and_saveexec_b64 s[0:1], s[2:3]
	s_or_b64 exec, exec, s[0:1]
	s_add_i32 s75, s76, 2
	s_cmpk_lt_u32 s76, 0x46
	s_cselect_b64 s[56:57], -1, 0
	s_cmpk_gt_u32 s76, 0x45
	s_cselect_b64 s[54:55], -1, 0
	s_and_b64 vcc, exec, s[54:55]
	s_waitcnt lgkmcnt(0)
	s_branch .LBB0_2429
.LBB0_2429:
	ds_read_b128 v[80:83], v160 offset:17408
	ds_read_b128 v[76:79], v160
	ds_read_b128 v[84:87], v160 offset:21760
	ds_read_b128 v[88:91], v160 offset:17472
	ds_read_b128 v[92:95], v160 offset:64
	ds_read_b128 v[96:99], v160 offset:4352
	ds_read_b128 v[100:103], v160 offset:21824
	ds_read_b128 v[104:107], v160 offset:4416
	s_waitcnt lgkmcnt(6)
	v_mfma_f32_16x16x32_bf16 v[76:79], v[80:83], v[76:79], 0
	v_cvt_pk_bf16_f32 v186, v52, v53
	v_cvt_pk_bf16_f32 v187, v54, v55
	v_cvt_pk_bf16_f32 v188, v56, v57
	s_waitcnt lgkmcnt(3)
	v_mfma_f32_16x16x32_bf16 v[76:79], v[88:91], v[92:95], v[76:79]
	ds_read_b128 v[92:95], v160 offset:17536
	ds_read_b128 v[108:111], v160 offset:128
	v_cvt_pk_bf16_f32 v189, v58, v59
	s_cmp_lt_u32 s76, 8
	s_waitcnt lgkmcnt(4)
	v_mfma_f32_16x16x32_bf16 v[84:87], v[84:87], v[96:99], 0
	s_cselect_b32 s77, 0xff, s58
	s_add_i32 s77, s77, s38
	s_add_i32 s78, s77, 32
	s_waitcnt lgkmcnt(2)
	v_mfma_f32_16x16x32_bf16 v[84:87], v[100:103], v[104:107], v[84:87]
	ds_read_b128 v[100:103], v160 offset:21888
	ds_read_b128 v[162:165], v160 offset:17600
	ds_read_b128 v[166:169], v160 offset:192
	ds_read_b128 v[170:173], v160 offset:4480
	ds_read_b128 v[174:177], v160 offset:21952
	ds_read_b128 v[178:181], v160 offset:4544
	s_and_b64 s[14:15], s[12:13], exec
	s_waitcnt lgkmcnt(6)
	v_mfma_f32_16x16x32_bf16 v[108:111], v[92:95], v[108:111], v[76:79]
	ds_read_u16 v0, v148 offset:8704
	ds_read_u16 v1, v148 offset:8976
	ds_read_u16 v3, v148 offset:9248
	ds_read_u16 v77, v148 offset:9520
	ds_read_u16 v78, v148 offset:13056
	ds_read_u16 v79, v148 offset:13328
	ds_read_u16 v125, v148 offset:13600
	ds_read_u16 v182, v148 offset:13872
	s_waitcnt lgkmcnt(6)
	v_lshl_or_b32 v76, v1, 16, v0
	v_mov_b32_e32 v0, s39
	v_mfma_f32_16x16x32_bf16 v[84:87], v[100:103], v[170:173], v[84:87]
	s_waitcnt lgkmcnt(2)
	v_lshl_or_b32 v78, v79, 16, v78
	s_waitcnt lgkmcnt(0)
	v_lshl_or_b32 v79, v182, 16, v125
	v_add_u32_e32 v125, 0x1000, v161
	v_mfma_f32_16x16x32_bf16 v[100:103], v[162:165], v[166:169], v[108:111]
	ds_read2_b64 v[166:169], v125 offset0:32 offset1:36
	v_lshl_or_b32 v77, v77, 16, v3
	s_cselect_b32 s14, s74, s78
	ds_read2_b64 v[108:111], v161 offset1:4
	v_mfma_f32_16x16x32_bf16 v[80:83], v[80:83], v[96:99], 0
	s_nop 2
	v_cndmask_b32_e64 v0, v100, v0, s[4:5]
	v_cndmask_b32_e64 v0, v0, v100, s[6:7]
	v_cndmask_b32_e64 v3, v102, 0, s[8:9]
	v_mfma_f32_16x16x32_bf16 v[84:87], v[174:177], v[178:181], v[84:87]
	v_cvt_pk_bf16_f32 v174, v44, v45
	v_cvt_pk_bf16_f32 v175, v46, v47
	v_cvt_pk_bf16_f32 v176, v48, v49
	v_cvt_pk_bf16_f32 v177, v50, v51
	v_mfma_f32_16x16x32_bf16 v[80:83], v[88:91], v[104:107], v[80:83]
	s_add_u32 s14, s50, s14
	s_addc_u32 s15, s51, 0
	s_lshl_b64 s[14:15], s[14:15], 11
	s_waitcnt lgkmcnt(0)
	v_mfma_f32_16x16x32_bf16 v[96:99], v[108:111], v[174:177], 0
	ds_read2_b64 v[108:111], v161 offset0:8 offset1:12
	ds_read2_b64 v[182:185], v125 offset0:40 offset1:44
	ds_read2_b64 v[88:91], v161 offset0:16 offset1:20
	ds_read2_b64 v[104:107], v125 offset0:48 offset1:52
	v_mfma_f32_16x16x32_bf16 v[166:169], v[166:169], v[174:177], 0
	v_cvt_pk_bf16_f32 v174, v60, v61
	v_cvt_pk_bf16_f32 v175, v62, v63
	v_cvt_pk_bf16_f32 v176, v64, v65
	s_waitcnt lgkmcnt(3)
; DI unsigned pack2(float lo, float hi) { const f32x2 v = (f32x2){lo, hi}; return __builtin_bit_cast(unsigned, __builtin_convertvector(v, bf16x2_t)); }
; DI void hgrn_scan_mfma(const Params& p, char* shm) {
;     ...
;                   o0 = __builtin_amdgcn_mfma_f32_16x16x32_bf16(__builtin_bit_cast(bf16x8, (u32x4){qa0.x, qa0.y, qb0.x, qb0.y}), sw, o0, 0, 0, 0);
;                   o1 = __builtin_amdgcn_mfma_f32_16x16x32_bf16(__builtin_bit_cast(bf16x8, (u32x4){qa1.x, qa1.y, qb1.x, qb1.y}), sw, o1, 0, 0, 0); }
; #pragma unroll
;               for (int r = 0; r < 4; ++r) if (g * 4 + r > l15) { sc00[r] = 0.f; sc11[r] = 0.f; }
;               o0 = __builtin_amdgcn_mfma_f32_16x16x32_bf16(__builtin_bit_cast(bf16x8, (u32x4){pack2(sc00[0], sc00[1]), pack2(sc00[2], sc00[3]), 0u, 0u}), vf, o0, 0, 0, 0);
;               o1 = __builtin_amdgcn_mfma_f32_16x16x32_bf16(__builtin_bit_cast(bf16x8, (u32x4){pack2(sc01[0], sc01[1]), pack2(sc01[2], sc01[3]), pack2(sc11[0], sc11[1]), pack2(sc11[2], sc11[3])}), vf, o1, 0, 0, 0);
; #pragma unroll
;               for (int r = 0; r < 4; ++r) {
;                   const long rb_ = (long)HG_ROW(b, dir, ch * C), st_ = dir ? -(long)D : (long)D; bf16_t* op_ = Oo + rb_ * D + head * 128 + vcol + (long)(g * 4 + r) * st_;
;                   op_[0] = (bf16_t)(pack2(o0[r], 0.f) & 0xffffu); op_[16 * st_] = (bf16_t)(pack2(o1[r], 0.f) & 0xffffu); }
	v_mfma_f32_16x16x32_bf16 v[96:99], v[108:111], v[186:189], v[96:99]
	v_cvt_pk_bf16_f32 v177, v66, v67
	v_mfma_f32_16x16x32_bf16 v[80:83], v[92:95], v[170:173], v[80:83]
	v_mov_b32_e32 v92, s39
	v_cndmask_b32_e64 v1, v84, v92, s[4:5]
	s_waitcnt lgkmcnt(2)
	v_mfma_f32_16x16x32_bf16 v[108:111], v[182:185], v[186:189], v[166:169]
	s_nop 2
	ds_read2_b64 v[166:169], v161 offset0:24 offset1:28
	ds_read2_b64 v[182:185], v125 offset0:56 offset1:60
	v_cvt_pk_bf16_f32 v186, v72, v73
	v_cvt_pk_bf16_f32 v187, v74, v75
	s_waitcnt lgkmcnt(3)
	v_mfma_f32_16x16x32_bf16 v[88:91], v[88:91], v[174:177], v[96:99]
	v_cvt_pk_bf16_f32 v188, v68, v69
	v_cvt_pk_bf16_f32 v189, v70, v71
	v_mfma_f32_16x16x32_bf16 v[80:83], v[162:165], v[178:181], v[80:83]
	v_cndmask_b32_e64 v96, v1, v84, s[6:7]
	v_cndmask_b32_e64 v1, 0, v101, s[6:7]
	v_cndmask_b32_e64 v84, v103, 0, s[10:11]
	s_waitcnt lgkmcnt(2)
	v_mfma_f32_16x16x32_bf16 v[92:95], v[104:107], v[174:177], v[108:111]
	v_cvt_pk_bf16_f32 v0, v0, v1
	v_cvt_pk_bf16_f32 v1, v3, v84
	v_mov_b32_e32 v3, v2
	v_cndmask_b32_e64 v97, 0, v85, s[6:7]
	v_cndmask_b32_e64 v98, v86, 0, s[8:9]
	v_cndmask_b32_e64 v99, v87, 0, s[10:11]
	s_waitcnt lgkmcnt(1)
	v_mfma_f32_16x16x32_bf16 v[88:91], v[166:169], v[186:189], v[88:91]
	v_cvt_pk_bf16_f32 v80, v80, v81
	v_cvt_pk_bf16_f32 v81, v82, v83
	v_cvt_pk_bf16_f32 v82, v96, v97
	v_cvt_pk_bf16_f32 v83, v98, v99
	s_waitcnt lgkmcnt(0)
	v_mfma_f32_16x16x32_bf16 v[92:95], v[182:185], v[186:189], v[92:95]
	v_mfma_f32_16x16x32_bf16 v[84:87], v[0:3], v[76:79], v[88:91]
	v_lshl_add_u64 v[0:1], v[132:133], 0, s[14:15]
	v_mfma_f32_16x16x32_bf16 v[80:83], v[80:83], v[76:79], v[92:95]
	s_nop 0
	v_lshl_add_u64 v[88:89], v[134:135], 1, v[0:1]
	s_nop 3
	v_cvt_pk_bf16_f32 v3, v84, s0
	global_store_short v[88:89], v3, off
	v_lshl_add_u64 v[88:89], v[88:89], 0, s[52:53]
	v_cvt_pk_bf16_f32 v3, v80, s0
	global_store_short v[88:89], v3, off
	v_lshl_add_u64 v[88:89], v[136:137], 1, v[0:1]
	v_cvt_pk_bf16_f32 v3, v85, s0
	global_store_short v[88:89], v3, off
	v_cvt_pk_bf16_f32 v3, v81, s0
	v_lshl_add_u64 v[80:81], v[88:89], 0, s[52:53]
	global_store_short v[80:81], v3, off
	v_lshl_add_u64 v[80:81], v[138:139], 1, v[0:1]
	v_cvt_pk_bf16_f32 v3, v86, s0
	global_store_short v[80:81], v3, off
	ds_read_u16 v3, v155 offset:17408
	ds_read_u16 v84, v155 offset:17440
	ds_read_u16 v85, v155 offset:17472
	ds_read_u16 v86, v155 offset:17504
	ds_read_u16 v96, v155 offset:17536
	ds_read_u16 v97, v155 offset:17568
	ds_read_u16 v98, v155 offset:17600
	ds_read_u16 v162, v155 offset:17632
	ds_read_u16 v88, v155 offset:17680
	ds_read_u16 v92, v155 offset:17712
	ds_read_u16 v99, v155 offset:17744
	ds_read_u16 v100, v155 offset:17776
	ds_read_u16 v101, v155 offset:17808
	ds_read_u16 v102, v155 offset:17840
	ds_read_u16 v103, v155 offset:17872
	ds_read_u16 v163, v155 offset:17904
	s_waitcnt lgkmcnt(7)
	v_lshl_or_b32 v88, v88, 16, v3
	ds_read_u16 v3, v155 offset:17952
	ds_read_u16 v93, v155 offset:17984
	ds_read_u16 v104, v155 offset:18016
	ds_read_u16 v105, v155 offset:18048
	ds_read_u16 v106, v155 offset:18080
	ds_read_u16 v107, v155 offset:18112
	ds_read_u16 v108, v155 offset:18144
	ds_read_u16 v164, v155 offset:18176
	ds_read_u16 v89, v155 offset:18224
	ds_read_u16 v94, v155 offset:18256
	ds_read_u16 v109, v155 offset:18288
	ds_read_u16 v110, v155 offset:18320
	ds_read_u16 v111, v155 offset:18352
	ds_read_u16 v165, v155 offset:18384
	ds_read_u16 v166, v155 offset:18416
	ds_read_u16 v167, v155 offset:18448
	s_waitcnt lgkmcnt(7)
	v_lshl_or_b32 v89, v89, 16, v3
	ds_read_u16 v3, v155 offset:21760
	ds_read_u16 v95, v155 offset:21792
	ds_read_u16 v168, v155 offset:21824
	ds_read_u16 v169, v155 offset:21856
	ds_read_u16 v170, v155 offset:21888
	ds_read_u16 v171, v155 offset:21920
	ds_read_u16 v172, v155 offset:21952
	ds_read_u16 v173, v155 offset:21984
	ds_read_u16 v90, v155 offset:22032
	ds_read_u16 v174, v155 offset:22064
	ds_read_u16 v175, v155 offset:22096
	ds_read_u16 v176, v155 offset:22128
	ds_read_u16 v177, v155 offset:22160
	ds_read_u16 v178, v155 offset:22192
	ds_read_u16 v179, v155 offset:22224
	ds_read_u16 v180, v155 offset:22256
	s_waitcnt lgkmcnt(7)
	v_lshl_or_b32 v90, v90, 16, v3
	ds_read_u16 v3, v155 offset:22304
	ds_read_u16 v181, v155 offset:22336
	ds_read_u16 v182, v155 offset:22368
	ds_read_u16 v183, v155 offset:22400
	ds_read_u16 v184, v155 offset:22432
	ds_read_u16 v185, v155 offset:22464
	ds_read_u16 v186, v155 offset:22496
	ds_read_u16 v187, v155 offset:22528
	ds_read_u16 v91, v155 offset:22576
	ds_read_u16 v188, v155 offset:22608
	ds_read_u16 v189, v155 offset:22640
	ds_read_u16 v190, v155 offset:22672
	ds_read_u16 v191, v155 offset:22704
	ds_read_u16 v192, v155 offset:22736
	ds_read_u16 v193, v155 offset:22768
	ds_read_u16 v194, v155 offset:22800
	s_waitcnt lgkmcnt(7)
	v_lshl_or_b32 v91, v91, 16, v3
	v_lshl_or_b32 v92, v92, 16, v84
	v_lshl_or_b32 v93, v94, 16, v93
	v_lshl_or_b32 v94, v174, 16, v95
	s_waitcnt lgkmcnt(6)
	v_lshl_or_b32 v95, v188, 16, v181
	v_mfma_f32_16x16x32_bf16 v[44:47], v[88:91], v[76:79], v[44:47]
	v_lshl_or_b32 v88, v99, 16, v85
	v_lshl_or_b32 v89, v109, 16, v104
	v_lshl_or_b32 v90, v175, 16, v168
	s_waitcnt lgkmcnt(5)
	v_lshl_or_b32 v91, v189, 16, v182
	v_cvt_pk_bf16_f32 v3, v82, s0
	v_lshl_add_u64 v[80:81], v[80:81], 0, s[52:53]
	global_store_short v[80:81], v3, off
	v_lshl_add_u64 v[0:1], v[140:141], 1, v[0:1]
	v_cvt_pk_bf16_f32 v3, v87, s0
	v_mfma_f32_16x16x32_bf16 v[48:51], v[92:95], v[76:79], v[48:51]
	v_lshl_or_b32 v92, v100, 16, v86
	v_lshl_or_b32 v93, v110, 16, v105
	v_lshl_or_b32 v94, v176, 16, v169
	s_waitcnt lgkmcnt(4)
; DI void hgrn_scan_mfma(const Params& p, char* shm) {
;     ...
;               for (int kt = 0; kt < 8; ++kt) { const f32x4 dcy = *(const f32x4*)(eBL + kt * 16 + g * 4); const int kcol = kt * 16 + l15;
;                   const bf16x8 kl = __builtin_bit_cast(bf16x8, (u32x4){HG_U2(kt16, g * 4 + 0, g * 4 + 1, kcol), HG_U2(kt16, g * 4 + 2, g * 4 + 3, kcol), HG_U2(kt16, 16 + g * 4 + 0, 16 + g * 4 + 1, kcol), HG_U2(kt16, 16 + g * 4 + 2, 16 + g * 4 + 3, kcol)});
;                   S[kt] = __builtin_amdgcn_mfma_f32_16x16x32_bf16(kl, vf, S[kt], 0, 0, 0) * dcy; }
	v_lshl_or_b32 v95, v190, 16, v183
	v_mfma_f32_16x16x32_bf16 v[52:55], v[88:91], v[76:79], v[52:55]
	global_store_short v[0:1], v3, off
	v_lshl_or_b32 v84, v101, 16, v96
	v_lshl_or_b32 v85, v111, 16, v106
	v_lshl_or_b32 v86, v177, 16, v170
	s_waitcnt lgkmcnt(3)
	v_lshl_or_b32 v87, v191, 16, v184
	v_lshl_or_b32 v88, v102, 16, v97
	v_lshl_or_b32 v89, v165, 16, v107
	v_lshl_or_b32 v90, v178, 16, v171
	s_waitcnt lgkmcnt(2)
	v_lshl_or_b32 v91, v192, 16, v185
	v_cvt_pk_bf16_f32 v3, v83, s0
	v_lshl_or_b32 v80, v103, 16, v98
	v_lshl_or_b32 v81, v166, 16, v108
	v_lshl_or_b32 v82, v179, 16, v172
	s_waitcnt lgkmcnt(1)
	v_lshl_or_b32 v83, v193, 16, v186
	v_lshl_or_b32 v162, v163, 16, v162
	v_lshl_or_b32 v163, v167, 16, v164
	v_lshl_or_b32 v164, v180, 16, v173
	s_waitcnt lgkmcnt(0)
	v_lshl_or_b32 v165, v194, 16, v187
	v_lshl_add_u64 v[0:1], v[0:1], 0, s[52:53]
	v_mfma_f32_16x16x32_bf16 v[56:59], v[92:95], v[76:79], v[56:59]
	global_store_short v[0:1], v3, off
	v_mfma_f32_16x16x32_bf16 v[60:63], v[84:87], v[76:79], v[60:63]
	ds_read_b128 v[108:111], v149 offset:26112
	ds_read_b128 v[104:107], v149 offset:26176
	ds_read_b128 v[100:103], v149 offset:26240
	ds_read_b128 v[96:99], v149 offset:26304
	v_mfma_f32_16x16x32_bf16 v[64:67], v[88:91], v[76:79], v[64:67]
	v_mfma_f32_16x16x32_bf16 v[80:83], v[80:83], v[76:79], v[72:75]
	ds_read_b128 v[92:95], v149 offset:26368
	ds_read_b128 v[88:91], v149 offset:26432
	ds_read_b128 v[84:87], v149 offset:26496
	ds_read_b128 v[72:75], v149 offset:26560
	s_waitcnt lgkmcnt(0)
	s_barrier
	v_mfma_f32_16x16x32_bf16 v[76:79], v[162:165], v[76:79], v[68:71]
	s_nop 0
	s_nop 0
	s_and_saveexec_b64 s[14:15], s[2:3]
	s_or_b64 exec, exec, s[14:15]
	s_andn2_b64 vcc, exec, s[56:57]
	s_waitcnt lgkmcnt(0)
	s_branch .LBB0_2441
.LBB0_2441:
	v_pk_mul_f32 v[58:59], v[98:99], v[58:59]
	v_pk_mul_f32 v[56:57], v[96:97], v[56:57]
	ds_read_b128 v[96:99], v160 offset:50176
	v_pk_mul_f32 v[62:63], v[94:95], v[62:63]
	v_pk_mul_f32 v[60:61], v[92:93], v[60:61]
	ds_read_b128 v[68:71], v160 offset:54528
	ds_read_b128 v[92:95], v160 offset:32768
	v_pk_mul_f32 v[46:47], v[110:111], v[46:47]
	v_pk_mul_f32 v[44:45], v[108:109], v[44:45]
	v_pk_mul_f32 v[50:51], v[106:107], v[50:51]
	v_pk_mul_f32 v[48:49], v[104:105], v[48:49]
	v_pk_mul_f32 v[54:55], v[102:103], v[54:55]
	v_pk_mul_f32 v[52:53], v[100:101], v[52:53]
	ds_read_b128 v[100:103], v160 offset:37120
	ds_read_b128 v[104:107], v160 offset:50240
	ds_read_b128 v[108:111], v160 offset:32832
	ds_read_b128 v[162:165], v160 offset:54592
	ds_read_b128 v[166:169], v160 offset:37184
	v_pk_mul_f32 v[66:67], v[90:91], v[66:67]
	s_waitcnt lgkmcnt(5)
	v_mfma_f32_16x16x32_bf16 v[90:93], v[96:99], v[92:95], 0
	v_mul_f32_e64 v64, v88, v64
	v_mul_f32_e64 v65, v89, v65
	v_pk_mul_f32 v[78:79], v[74:75], v[78:79]
	v_pk_mul_f32 v[76:77], v[72:73], v[76:77]
	s_waitcnt lgkmcnt(4)
	v_mfma_f32_16x16x32_bf16 v[170:173], v[68:71], v[100:103], 0
	v_mul_f32_e64 v70, v86, v82
	v_mul_f32_e64 v71, v87, v83
	v_pk_mul_f32 v[68:69], v[84:85], v[80:81]
	ds_read_b128 v[84:87], v160 offset:50304
	s_waitcnt lgkmcnt(3)
	v_mfma_f32_16x16x32_bf16 v[80:83], v[104:107], v[108:111], v[90:93]
	s_nop 2
	ds_read_b128 v[88:91], v160 offset:54656
	ds_read_b128 v[92:95], v160 offset:32896
	v_cvt_pk_bf16_f32 v186, v52, v53
	v_cvt_pk_bf16_f32 v187, v54, v55
	s_waitcnt lgkmcnt(3)
	v_mfma_f32_16x16x32_bf16 v[108:111], v[162:165], v[166:169], v[170:173]
	ds_read_b128 v[162:165], v160 offset:37248
	s_nop 1
	ds_read_b128 v[170:173], v160 offset:50368
	ds_read_b128 v[174:177], v160 offset:32960
	ds_read_b128 v[72:75], v160 offset:54720
	ds_read_b128 v[178:181], v160 offset:37312
	v_cvt_pk_bf16_f32 v188, v56, v57
	s_waitcnt lgkmcnt(4)
	v_mfma_f32_16x16x32_bf16 v[88:91], v[88:91], v[162:165], v[108:111]
	v_cvt_pk_bf16_f32 v189, v58, v59
	s_add_i32 s14, s74, 32
	s_and_b64 s[0:1], s[12:13], exec
	v_mfma_f32_16x16x32_bf16 v[92:95], v[84:87], v[92:95], v[80:83]
	ds_read_u16 v0, v148 offset:41472
	ds_read_u16 v1, v148 offset:41744
	ds_read_u16 v3, v148 offset:42016
	ds_read_u16 v81, v148 offset:42288
	ds_read_u16 v82, v148 offset:45824
	ds_read_u16 v83, v148 offset:46096
	ds_read_u16 v182, v148 offset:46368
	ds_read_u16 v183, v148 offset:46640
	ds_read2_b64 v[108:111], v195 offset1:4
	s_waitcnt lgkmcnt(7)
	v_lshl_or_b32 v80, v1, 16, v0
	v_mfma_f32_16x16x32_bf16 v[72:75], v[72:75], v[178:181], v[88:91]
	s_waitcnt lgkmcnt(3)
	v_lshl_or_b32 v82, v83, 16, v82
	s_waitcnt lgkmcnt(1)
	v_lshl_or_b32 v83, v183, 16, v182
	v_mov_b32_e32 v0, s39
	ds_read2_b64 v[88:91], v197 offset0:32 offset1:36
	v_mfma_f32_16x16x32_bf16 v[96:99], v[96:99], v[100:103], 0
	v_lshl_or_b32 v81, v81, 16, v3
	s_cselect_b32 s0, s14, s77
	s_add_u32 s0, s50, s0
	v_mfma_f32_16x16x32_bf16 v[92:95], v[170:173], v[174:177], v[92:95]
	v_cvt_pk_bf16_f32 v174, v44, v45
	v_cvt_pk_bf16_f32 v175, v46, v47
	v_cvt_pk_bf16_f32 v176, v48, v49
	v_cvt_pk_bf16_f32 v177, v50, v51
	v_mfma_f32_16x16x32_bf16 v[96:99], v[104:107], v[166:169], v[96:99]
	s_nop 2
	v_cndmask_b32_e64 v0, v92, v0, s[4:5]
	v_cndmask_b32_e64 v0, v0, v92, s[6:7]
	v_cndmask_b32_e64 v3, v94, 0, s[8:9]
	s_waitcnt lgkmcnt(1)
	v_mfma_f32_16x16x32_bf16 v[100:103], v[108:111], v[174:177], 0
	ds_read2_b64 v[108:111], v195 offset0:8 offset1:12
	ds_read2_b64 v[182:185], v197 offset0:40 offset1:44
	ds_read2_b64 v[104:107], v195 offset0:16 offset1:20
	ds_read2_b64 v[166:169], v197 offset0:48 offset1:52
	s_addc_u32 s1, s51, 0
	s_waitcnt lgkmcnt(4)
	v_mfma_f32_16x16x32_bf16 v[88:91], v[88:91], v[174:177], 0
	v_cvt_pk_bf16_f32 v174, v60, v61
	v_cvt_pk_bf16_f32 v175, v62, v63
	v_cvt_pk_bf16_f32 v176, v64, v65
	s_waitcnt lgkmcnt(3)
; DI unsigned pack2(float lo, float hi) { const f32x2 v = (f32x2){lo, hi}; return __builtin_bit_cast(unsigned, __builtin_convertvector(v, bf16x2_t)); }
; DI void hgrn_scan_mfma(const Params& p, char* shm) {
;     ...
;               o0 = __builtin_amdgcn_mfma_f32_16x16x32_bf16(__builtin_bit_cast(bf16x8, (u32x4){pack2(sc00[0], sc00[1]), pack2(sc00[2], sc00[3]), 0u, 0u}), vf, o0, 0, 0, 0);
;               o1 = __builtin_amdgcn_mfma_f32_16x16x32_bf16(__builtin_bit_cast(bf16x8, (u32x4){pack2(sc01[0], sc01[1]), pack2(sc01[2], sc01[3]), pack2(sc11[0], sc11[1]), pack2(sc11[2], sc11[3])}), vf, o1, 0, 0, 0);
; #pragma unroll
;               for (int r = 0; r < 4; ++r) {
;                   const long rb_ = (long)HG_ROW(b, dir, ch * C), st_ = dir ? -(long)D : (long)D; bf16_t* op_ = Oo + rb_ * D + head * 128 + vcol + (long)(g * 4 + r) * st_;
;                   op_[0] = (bf16_t)(pack2(o0[r], 0.f) & 0xffffu); op_[16 * st_] = (bf16_t)(pack2(o1[r], 0.f) & 0xffffu); }
; #pragma unroll
;               for (int kt = 0; kt < 8; ++kt) { const f32x4 dcy = *(const f32x4*)(eBL + kt * 16 + g * 4); const int kcol = kt * 16 + l15;
;                   const bf16x8 kl = __builtin_bit_cast(bf16x8, (u32x4){HG_U2(kt16, g * 4 + 0, g * 4 + 1, kcol), HG_U2(kt16, g * 4 + 2, g * 4 + 3, kcol), HG_U2(kt16, 16 + g * 4 + 0, 16 + g * 4 + 1, kcol), HG_U2(kt16, 16 + g * 4 + 2, 16 + g * 4 + 3, kcol)});
;                   S[kt] = __builtin_amdgcn_mfma_f32_16x16x32_bf16(kl, vf, S[kt], 0, 0, 0) * dcy; }
	v_mfma_f32_16x16x32_bf16 v[100:103], v[108:111], v[186:189], v[100:103]
	v_cvt_pk_bf16_f32 v177, v66, v67
	s_lshl_b64 s[0:1], s[0:1], 11
	v_mfma_f32_16x16x32_bf16 v[84:87], v[84:87], v[162:165], v[96:99]
	s_sub_i32 s38, s38, 64
	s_add_i32 s74, s74, 64
	s_and_b64 vcc, exec, s[54:55]
	s_waitcnt lgkmcnt(2)
	v_mfma_f32_16x16x32_bf16 v[88:91], v[182:185], v[186:189], v[88:91]
	ds_read2_b64 v[108:111], v195 offset0:24 offset1:28
	ds_read2_b64 v[182:185], v197 offset0:56 offset1:60
	v_cvt_pk_bf16_f32 v186, v68, v69
	v_cvt_pk_bf16_f32 v187, v70, v71
	s_waitcnt lgkmcnt(3)
	v_mfma_f32_16x16x32_bf16 v[96:99], v[104:107], v[174:177], v[100:103]
	v_cvt_pk_bf16_f32 v188, v76, v77
	v_cvt_pk_bf16_f32 v189, v78, v79
	s_nop 0
	v_mov_b32_e32 v100, s39
	v_mfma_f32_16x16x32_bf16 v[84:87], v[170:173], v[178:181], v[84:87]
	v_cndmask_b32_e64 v1, v72, v100, s[4:5]
	v_cndmask_b32_e64 v100, v1, v72, s[6:7]
	v_cndmask_b32_e64 v1, 0, v93, s[6:7]
	s_waitcnt lgkmcnt(2)
	v_mfma_f32_16x16x32_bf16 v[88:91], v[166:169], v[174:177], v[88:91]
	v_cndmask_b32_e64 v72, v95, 0, s[10:11]
	v_cvt_pk_bf16_f32 v0, v0, v1
	v_cvt_pk_bf16_f32 v1, v3, v72
	s_waitcnt lgkmcnt(1)
	v_mfma_f32_16x16x32_bf16 v[92:95], v[108:111], v[186:189], v[96:99]
	v_mov_b32_e32 v3, v2
	v_cvt_pk_bf16_f32 v84, v84, v85
	v_cvt_pk_bf16_f32 v85, v86, v87
	v_cndmask_b32_e64 v96, 0, v73, s[6:7]
	v_cndmask_b32_e64 v97, v74, 0, s[8:9]
	v_cndmask_b32_e64 v98, v75, 0, s[10:11]
	v_cvt_pk_bf16_f32 v86, v100, v96
	v_cvt_pk_bf16_f32 v87, v97, v98
	s_waitcnt lgkmcnt(0)
	v_mfma_f32_16x16x32_bf16 v[88:91], v[182:185], v[186:189], v[88:91]
	v_mfma_f32_16x16x32_bf16 v[72:75], v[0:3], v[80:83], v[92:95]
	v_lshl_add_u64 v[0:1], v[132:133], 0, s[0:1]
	v_mfma_f32_16x16x32_bf16 v[84:87], v[84:87], v[80:83], v[88:91]
	s_nop 4
	v_lshl_add_u64 v[88:89], v[134:135], 1, v[0:1]
	v_cvt_pk_bf16_f32 v3, v72, s0
	global_store_short v[88:89], v3, off
	v_cvt_pk_bf16_f32 v3, v84, s0
	v_lshl_add_u64 v[88:89], v[88:89], 0, s[52:53]
	global_store_short v[88:89], v3, off
	v_lshl_add_u64 v[88:89], v[136:137], 1, v[0:1]
	v_cvt_pk_bf16_f32 v3, v73, s0
	global_store_short v[88:89], v3, off
	v_cvt_pk_bf16_f32 v3, v85, s0
	v_lshl_add_u64 v[72:73], v[88:89], 0, s[52:53]
	global_store_short v[72:73], v3, off
	v_lshl_add_u64 v[72:73], v[138:139], 1, v[0:1]
	v_cvt_pk_bf16_f32 v3, v74, s0
	global_store_short v[72:73], v3, off
	v_cvt_pk_bf16_f32 v3, v86, s0
	v_lshl_add_u64 v[72:73], v[72:73], 0, s[52:53]
	global_store_short v[72:73], v3, off
	v_lshl_add_u64 v[0:1], v[140:141], 1, v[0:1]
	v_cvt_pk_bf16_f32 v3, v75, s0
	global_store_short v[0:1], v3, off
	v_cvt_pk_bf16_f32 v3, v87, s0
	v_lshl_add_u64 v[0:1], v[0:1], 0, s[52:53]
	global_store_short v[0:1], v3, off
	ds_read_b128 v[72:75], v149 offset:58880
	ds_read_u16 v0, v155 offset:50176
	ds_read_u16 v1, v155 offset:50208
	ds_read_u16 v3, v155 offset:50240
	ds_read_u16 v92, v155 offset:50272
	ds_read_u16 v93, v155 offset:50304
	ds_read_u16 v94, v155 offset:50336
	ds_read_u16 v95, v155 offset:50368
	ds_read_u16 v96, v155 offset:50400
	ds_read_u16 v84, v155 offset:50448
	ds_read_u16 v88, v155 offset:50480
	ds_read_u16 v97, v155 offset:50512
	ds_read_u16 v98, v155 offset:50544
	ds_read_u16 v99, v155 offset:50576
	ds_read_u16 v100, v155 offset:50608
	ds_read_u16 v101, v155 offset:50640
	ds_read_u16 v102, v155 offset:50672
	s_waitcnt lgkmcnt(7)
	v_lshl_or_b32 v84, v84, 16, v0
	ds_read_u16 v0, v155 offset:50720
	ds_read_u16 v89, v155 offset:50752
	ds_read_u16 v103, v155 offset:50784
	ds_read_u16 v104, v155 offset:50816
	ds_read_u16 v105, v155 offset:50848
	ds_read_u16 v106, v155 offset:50880
	ds_read_u16 v107, v155 offset:50912
	ds_read_u16 v108, v155 offset:50944
	ds_read_u16 v85, v155 offset:50992
	ds_read_u16 v90, v155 offset:51024
	ds_read_u16 v109, v155 offset:51056
	ds_read_u16 v110, v155 offset:51088
	ds_read_u16 v111, v155 offset:51120
	ds_read_u16 v125, v155 offset:51152
	ds_read_u16 v162, v155 offset:51184
	ds_read_u16 v163, v155 offset:51216
	s_waitcnt lgkmcnt(7)
	v_lshl_or_b32 v85, v85, 16, v0
	ds_read_u16 v0, v155 offset:54528
	ds_read_u16 v91, v155 offset:54560
	ds_read_u16 v164, v155 offset:54592
	ds_read_u16 v165, v155 offset:54624
	ds_read_u16 v166, v155 offset:54656
	ds_read_u16 v167, v155 offset:54688
	ds_read_u16 v168, v155 offset:54720
	ds_read_u16 v169, v155 offset:54752
	ds_read_u16 v86, v155 offset:54800
	ds_read_u16 v170, v155 offset:54832
	ds_read_u16 v171, v155 offset:54864
	ds_read_u16 v172, v155 offset:54896
	ds_read_u16 v173, v155 offset:54928
	ds_read_u16 v174, v155 offset:54960
	ds_read_u16 v175, v155 offset:54992
	ds_read_u16 v176, v155 offset:55024
	s_waitcnt lgkmcnt(7)
	v_lshl_or_b32 v86, v86, 16, v0
	ds_read_u16 v0, v155 offset:55072
	ds_read_u16 v177, v155 offset:55104
	ds_read_u16 v178, v155 offset:55136
	ds_read_u16 v179, v155 offset:55168
	ds_read_u16 v180, v155 offset:55200
	ds_read_u16 v181, v155 offset:55232
	ds_read_u16 v182, v155 offset:55264
	ds_read_u16 v183, v155 offset:55296
	ds_read_u16 v87, v155 offset:55344
	ds_read_u16 v184, v155 offset:55376
	ds_read_u16 v185, v155 offset:55408
	ds_read_u16 v186, v155 offset:55440
	ds_read_u16 v187, v155 offset:55472
	ds_read_u16 v188, v155 offset:55504
	ds_read_u16 v189, v155 offset:55536
	ds_read_u16 v190, v155 offset:55568
	s_waitcnt lgkmcnt(7)
	v_lshl_or_b32 v87, v87, 16, v0
	v_lshl_or_b32 v88, v88, 16, v1
	v_lshl_or_b32 v89, v90, 16, v89
	v_lshl_or_b32 v90, v170, 16, v91
	s_waitcnt lgkmcnt(6)
	v_lshl_or_b32 v91, v184, 16, v177
	v_mfma_f32_16x16x32_bf16 v[44:47], v[84:87], v[80:83], v[44:47]
	ds_read_b128 v[84:87], v149 offset:58944
	v_mfma_f32_16x16x32_bf16 v[48:51], v[88:91], v[80:83], v[48:51]
	v_lshl_or_b32 v88, v98, 16, v92
	s_nop 4
	v_pk_mul_f32 v[46:47], v[74:75], v[46:47]
	v_pk_mul_f32 v[44:45], v[72:73], v[44:45]
	ds_read_b128 v[72:75], v149 offset:59008
	v_lshl_or_b32 v89, v110, 16, v104
	s_waitcnt lgkmcnt(1)
; DI void hgrn_scan_mfma(const Params& p, char* shm) {
;     ...
;               for (int kt = 0; kt < 8; ++kt) { const f32x4 dcy = *(const f32x4*)(eBL + kt * 16 + g * 4); const int kcol = kt * 16 + l15;
;                   const bf16x8 kl = __builtin_bit_cast(bf16x8, (u32x4){HG_U2(kt16, g * 4 + 0, g * 4 + 1, kcol), HG_U2(kt16, g * 4 + 2, g * 4 + 3, kcol), HG_U2(kt16, 16 + g * 4 + 0, 16 + g * 4 + 1, kcol), HG_U2(kt16, 16 + g * 4 + 2, 16 + g * 4 + 3, kcol)});
;                   S[kt] = __builtin_amdgcn_mfma_f32_16x16x32_bf16(kl, vf, S[kt], 0, 0, 0) * dcy; }
	v_pk_mul_f32 v[50:51], v[86:87], v[50:51]
	v_pk_mul_f32 v[48:49], v[84:85], v[48:49]
	v_lshl_or_b32 v84, v97, 16, v3
	v_lshl_or_b32 v85, v109, 16, v103
	v_lshl_or_b32 v86, v171, 16, v164
	v_lshl_or_b32 v87, v185, 16, v178
	v_lshl_or_b32 v90, v172, 16, v165
	v_lshl_or_b32 v91, v186, 16, v179
	v_mfma_f32_16x16x32_bf16 v[52:55], v[84:87], v[80:83], v[52:55]
	ds_read_b128 v[84:87], v149 offset:59072
	v_mfma_f32_16x16x32_bf16 v[56:59], v[88:91], v[80:83], v[56:59]
	s_waitcnt lgkmcnt(1)
	s_nop 4
	v_pk_mul_f32 v[54:55], v[74:75], v[54:55]
	v_pk_mul_f32 v[52:53], v[72:73], v[52:53]
	ds_read_b128 v[72:75], v149 offset:59136
	v_lshl_or_b32 v88, v100, 16, v94
	v_lshl_or_b32 v89, v125, 16, v106
	s_waitcnt lgkmcnt(1)
	v_pk_mul_f32 v[58:59], v[86:87], v[58:59]
	v_pk_mul_f32 v[56:57], v[84:85], v[56:57]
	v_lshl_or_b32 v84, v99, 16, v93
	v_lshl_or_b32 v85, v111, 16, v105
	v_lshl_or_b32 v86, v173, 16, v166
	v_lshl_or_b32 v87, v187, 16, v180
	v_lshl_or_b32 v90, v174, 16, v167
	v_lshl_or_b32 v91, v188, 16, v181
	v_mfma_f32_16x16x32_bf16 v[60:63], v[84:87], v[80:83], v[60:63]
	ds_read_b128 v[84:87], v149 offset:59200
	v_mfma_f32_16x16x32_bf16 v[64:67], v[88:91], v[80:83], v[64:67]
	s_waitcnt lgkmcnt(1)
	s_nop 4
	v_pk_mul_f32 v[62:63], v[74:75], v[62:63]
	v_pk_mul_f32 v[60:61], v[72:73], v[60:61]
	ds_read_b128 v[72:75], v149 offset:59264
	v_lshl_or_b32 v88, v102, 16, v96
	v_lshl_or_b32 v89, v163, 16, v108
	s_waitcnt lgkmcnt(1)
	v_pk_mul_f32 v[66:67], v[86:87], v[66:67]
	v_pk_mul_f32 v[64:65], v[84:85], v[64:65]
	v_lshl_or_b32 v84, v101, 16, v95
	v_lshl_or_b32 v85, v162, 16, v107
	v_lshl_or_b32 v86, v175, 16, v168
	v_lshl_or_b32 v87, v189, 16, v182
	v_lshl_or_b32 v90, v176, 16, v169
	v_lshl_or_b32 v91, v190, 16, v183
	v_mfma_f32_16x16x32_bf16 v[68:71], v[84:87], v[80:83], v[68:71]
	ds_read_b128 v[84:87], v149 offset:59328
	s_waitcnt lgkmcnt(1)
	s_nop 5
	v_pk_mul_f32 v[74:75], v[74:75], v[70:71]
	v_pk_mul_f32 v[72:73], v[72:73], v[68:69]
	v_mfma_f32_16x16x32_bf16 v[68:71], v[88:91], v[80:83], v[76:79]
	s_waitcnt lgkmcnt(0)
	s_nop 6
	v_pk_mul_f32 v[70:71], v[86:87], v[70:71]
	v_pk_mul_f32 v[68:69], v[84:85], v[68:69]
	s_cbranch_vccnz .LBB0_2411
	s_mov_b32 s76, s75
	s_branch .LBB0_2417
.Lscanh_pro:
	v_cmp_gt_u32_e32 vcc, 0x120, v252
	s_mov_b64 s[2:3], vcc
	s_and_b32 s101, s48, 32
	s_sub_u32 s101, s101, 16
	v_add_u32_e32 v228, 0xffffef00, v158
	v_add_u32_e32 v229, 0xfffff000, v159
	v_add_co_u32_e32 v250, vcc, 0xffffc000, v144
	s_nop 1
	v_addc_co_u32_e32 v251, vcc, -1, v145, vcc
	v_cndmask_b32_e64 v0, v150, v113, s[12:13]
	v_add_u32_e32 v0, s101, v0
	v_ashrrev_i32_e32 v1, 31, v0
	v_lshl_add_u64 v[0:1], s[50:51], 0, v[0:1]
	v_lshlrev_b64 v[196:197], 12, v[0:1]
	v_lshlrev_b64 v[0:1], 11, v[0:1]
	v_lshl_add_u64 v[198:199], v[128:129], 0, v[0:1]
	v_lshl_add_u64 v[208:209], v[142:143], 0, v[196:197]
	v_lshl_add_u64 v[0:1], v[130:131], 0, v[0:1]
	global_load_dwordx4 v[196:199], v[198:199], off
	s_nop 0
	global_load_dwordx4 v[200:203], v[208:209], off
	global_load_dwordx4 v[204:207], v[0:1], off
	s_nop 0
	global_load_dwordx4 v[208:211], v[208:209], off offset:2048
	s_and_saveexec_b64 s[14:15], s[2:3]
	s_cbranch_execz .Lscanh_ep0
	global_load_dwordx4 v[4:7], v[250:251], off
.Lscanh_ep0:
	s_or_b64 exec, exec, s[14:15]
	v_add_co_u32_e32 v250, vcc, 0x1000, v250
	s_nop 1
	v_addc_co_u32_e32 v251, vcc, 0, v251, vcc
	v_cndmask_b32_e64 v0, v151, v146, s[12:13]
	v_add_u32_e32 v0, s101, v0
	v_ashrrev_i32_e32 v1, 31, v0
	v_lshl_add_u64 v[0:1], s[50:51], 0, v[0:1]
	v_lshlrev_b64 v[212:213], 12, v[0:1]
	v_lshlrev_b64 v[0:1], 11, v[0:1]
	v_lshl_add_u64 v[214:215], v[128:129], 0, v[0:1]
	v_lshl_add_u64 v[224:225], v[142:143], 0, v[212:213]
	v_lshl_add_u64 v[0:1], v[130:131], 0, v[0:1]
	global_load_dwordx4 v[212:215], v[214:215], off
	s_nop 0
	global_load_dwordx4 v[216:219], v[224:225], off
	global_load_dwordx4 v[220:223], v[0:1], off
	s_nop 0
	global_load_dwordx4 v[224:227], v[224:225], off offset:2048
	s_and_saveexec_b64 s[14:15], s[2:3]
	s_cbranch_execz .Lscanh_ep1
	global_load_dwordx4 v[8:11], v[250:251], off
.Lscanh_ep1:
	s_or_b64 exec, exec, s[14:15]
	v_add_co_u32_e32 v250, vcc, 0x1000, v250
	s_nop 1
	v_addc_co_u32_e32 v251, vcc, 0, v251, vcc
	s_waitcnt vmcnt(4)
.Lscanh_loop:
	s_waitcnt vmcnt(8)
	v_lshlrev_b32_e32 v80, 16, v12
	v_and_b32_e32 v81, 0xffff0000, v12
	v_lshlrev_b32_e32 v82, 16, v16
	v_and_b32_e32 v83, 0xffff0000, v16
	v_lshlrev_b32_e32 v84, 16, v13
	v_and_b32_e32 v85, 0xffff0000, v13
	v_lshlrev_b32_e32 v86, 16, v17
	v_and_b32_e32 v87, 0xffff0000, v17
	v_pk_mul_f32 v[80:81], v[80:81], v[82:83]
	v_pk_mul_f32 v[84:85], v[84:85], v[86:87]
	v_cvt_pk_bf16_f32 v76, v80, v81
	v_cvt_pk_bf16_f32 v77, v84, v85
	v_lshlrev_b32_e32 v80, 16, v14
	v_and_b32_e32 v81, 0xffff0000, v14
	v_lshlrev_b32_e32 v82, 16, v18
	v_and_b32_e32 v83, 0xffff0000, v18
	v_lshlrev_b32_e32 v84, 16, v15
	v_and_b32_e32 v85, 0xffff0000, v15
	v_lshlrev_b32_e32 v86, 16, v19
	v_and_b32_e32 v87, 0xffff0000, v19
	v_pk_mul_f32 v[80:81], v[80:81], v[82:83]
	v_pk_mul_f32 v[84:85], v[84:85], v[86:87]
	v_cvt_pk_bf16_f32 v78, v80, v81
	v_cvt_pk_bf16_f32 v79, v84, v85
	v_lshlrev_b32_e32 v80, 16, v196
	v_and_b32_e32 v81, 0xffff0000, v196
	v_lshlrev_b32_e32 v82, 16, v200
	v_and_b32_e32 v83, 0xffff0000, v200
	v_lshlrev_b32_e32 v84, 16, v197
	v_and_b32_e32 v85, 0xffff0000, v197
	v_lshlrev_b32_e32 v86, 16, v201
	v_and_b32_e32 v87, 0xffff0000, v201
	v_pk_mul_f32 v[80:81], v[80:81], v[82:83]
	v_pk_mul_f32 v[84:85], v[84:85], v[86:87]
	v_cvt_pk_bf16_f32 v246, v80, v81
	v_cvt_pk_bf16_f32 v247, v84, v85
	v_lshlrev_b32_e32 v80, 16, v198
	v_and_b32_e32 v81, 0xffff0000, v198
	v_lshlrev_b32_e32 v82, 16, v202
	v_and_b32_e32 v83, 0xffff0000, v202
	v_lshlrev_b32_e32 v84, 16, v199
	v_and_b32_e32 v85, 0xffff0000, v199
	v_lshlrev_b32_e32 v86, 16, v203
	v_and_b32_e32 v87, 0xffff0000, v203
	v_pk_mul_f32 v[80:81], v[80:81], v[82:83]
	v_pk_mul_f32 v[84:85], v[84:85], v[86:87]
	v_cvt_pk_bf16_f32 v248, v80, v81
	v_cvt_pk_bf16_f32 v249, v84, v85
	ds_write_b128 v158, v[76:79]
	ds_write_b128 v158, v[20:23] offset:8704
	ds_write_b128 v158, v[24:27] offset:17408
	ds_write_b128 v228, v[246:249]
	ds_write_b128 v228, v[204:207] offset:8704
	ds_write_b128 v228, v[208:211] offset:17408
	s_and_saveexec_b64 s[14:15], s[2:3]
	ds_write_b128 v229, v[4:7] offset:26112
	s_or_b64 exec, exec, s[14:15]
	s_add_i32 s75, s76, 2
	s_cmpk_lt_u32 s76, 0x46
	s_cselect_b64 s[56:57], -1, 0
	s_cmpk_gt_u32 s76, 0x45
	s_cselect_b64 s[54:55], -1, 0
	s_waitcnt lgkmcnt(0)
	s_barrier
	s_and_b64 vcc, exec, s[54:55]
	s_cbranch_vccnz .Lscanh_nopfa
	s_and_b64 vcc, exec, s[12:13]
	v_lshl_add_u32 v0, s75, 5, v113
	s_cbranch_vccnz .Lscanh_ia
	v_add3_u32 v1, v113, s74, 64
	v_cmp_lt_i32_e32 vcc, s47, v1
	s_and_saveexec_b64 s[14:15], vcc
	s_xor_b64 s[14:15], exec, s[14:15]
	v_add_u32_e32 v0, s38, v156
	v_add_u32_e32 v0, 0x9df, v0
	s_andn2_saveexec_b64 s[14:15], s[14:15]
	v_sub_u32_e32 v0, 0xff, v0
	s_or_b64 exec, exec, s[14:15]
.Lscanh_ia:
	v_add_u32_e32 v195, s101, v0
	v_ashrrev_i32_e32 v1, 31, v0
	v_lshl_add_u64 v[0:1], s[50:51], 0, v[0:1]
	v_lshlrev_b64 v[12:13], 12, v[0:1]
	v_lshlrev_b64 v[0:1], 11, v[0:1]
	v_lshl_add_u64 v[14:15], v[128:129], 0, v[0:1]
	v_lshl_add_u64 v[24:25], v[142:143], 0, v[12:13]
	v_lshl_add_u64 v[0:1], v[130:131], 0, v[0:1]
	global_load_dwordx4 v[12:15], v[14:15], off
	s_nop 0
	global_load_dwordx4 v[16:19], v[24:25], off
	global_load_dwordx4 v[20:23], v[0:1], off
	s_nop 0
	global_load_dwordx4 v[24:27], v[24:25], off offset:2048
	v_mov_b32_e32 v0, v195
	v_ashrrev_i32_e32 v1, 31, v0
	v_lshl_add_u64 v[0:1], s[50:51], 0, v[0:1]
	v_lshlrev_b64 v[196:197], 12, v[0:1]
	v_lshlrev_b64 v[0:1], 11, v[0:1]
	v_lshl_add_u64 v[198:199], v[128:129], 0, v[0:1]
	v_lshl_add_u64 v[208:209], v[142:143], 0, v[196:197]
	v_lshl_add_u64 v[0:1], v[130:131], 0, v[0:1]
	global_load_dwordx4 v[196:199], v[198:199], off
	s_nop 0
	global_load_dwordx4 v[200:203], v[208:209], off
	global_load_dwordx4 v[204:207], v[0:1], off
	s_nop 0
	global_load_dwordx4 v[208:211], v[208:209], off offset:2048
	s_and_saveexec_b64 s[14:15], s[2:3]
	s_cbranch_execz .Lscanh_ea
	global_load_dwordx4 v[4:7], v[250:251], off
.Lscanh_ea:
	s_or_b64 exec, exec, s[14:15]
	v_add_co_u32_e32 v250, vcc, 0x1000, v250
	s_nop 1
	v_addc_co_u32_e32 v251, vcc, 0, v251, vcc
.Lscanh_nopfa:
	s_and_b64 vcc, exec, s[54:55]
	s_cbranch_vccz .Lscanh_steady
	s_waitcnt vmcnt(0)
.Lscanh_steady:
	s_waitcnt vmcnt(8)
	v_lshlrev_b32_e32 v80, 16, v28
	v_and_b32_e32 v81, 0xffff0000, v28
	v_lshlrev_b32_e32 v82, 16, v32
	v_and_b32_e32 v83, 0xffff0000, v32
	v_lshlrev_b32_e32 v84, 16, v29
	v_and_b32_e32 v85, 0xffff0000, v29
	v_lshlrev_b32_e32 v86, 16, v33
	v_and_b32_e32 v87, 0xffff0000, v33
	v_pk_mul_f32 v[80:81], v[80:81], v[82:83]
	v_pk_mul_f32 v[84:85], v[84:85], v[86:87]
	v_cvt_pk_bf16_f32 v68, v80, v81
	v_cvt_pk_bf16_f32 v69, v84, v85
	v_lshlrev_b32_e32 v80, 16, v30
	v_and_b32_e32 v81, 0xffff0000, v30
	v_lshlrev_b32_e32 v82, 16, v34
	v_and_b32_e32 v83, 0xffff0000, v34
	v_lshlrev_b32_e32 v84, 16, v31
	v_and_b32_e32 v85, 0xffff0000, v31
	v_lshlrev_b32_e32 v86, 16, v35
	v_and_b32_e32 v87, 0xffff0000, v35
	v_pk_mul_f32 v[80:81], v[80:81], v[82:83]
	v_pk_mul_f32 v[84:85], v[84:85], v[86:87]
	v_cvt_pk_bf16_f32 v70, v80, v81
	v_cvt_pk_bf16_f32 v71, v84, v85
	v_lshlrev_b32_e32 v80, 16, v212
	v_and_b32_e32 v81, 0xffff0000, v212
	v_lshlrev_b32_e32 v82, 16, v216
	v_and_b32_e32 v83, 0xffff0000, v216
	v_lshlrev_b32_e32 v84, 16, v213
	v_and_b32_e32 v85, 0xffff0000, v213
	v_lshlrev_b32_e32 v86, 16, v217
	v_and_b32_e32 v87, 0xffff0000, v217
	v_pk_mul_f32 v[80:81], v[80:81], v[82:83]
	v_pk_mul_f32 v[84:85], v[84:85], v[86:87]
	v_cvt_pk_bf16_f32 v246, v80, v81
	v_cvt_pk_bf16_f32 v247, v84, v85
	v_lshlrev_b32_e32 v80, 16, v214
	v_and_b32_e32 v81, 0xffff0000, v214
	v_lshlrev_b32_e32 v82, 16, v218
	v_and_b32_e32 v83, 0xffff0000, v218
	v_lshlrev_b32_e32 v84, 16, v215
	v_and_b32_e32 v85, 0xffff0000, v215
	v_lshlrev_b32_e32 v86, 16, v219
	v_and_b32_e32 v87, 0xffff0000, v219
	v_pk_mul_f32 v[80:81], v[80:81], v[82:83]
	v_pk_mul_f32 v[84:85], v[84:85], v[86:87]
	v_cvt_pk_bf16_f32 v248, v80, v81
	v_cvt_pk_bf16_f32 v249, v84, v85
	ds_write_b128 v158, v[68:71] offset:32768
	ds_write_b128 v158, v[36:39] offset:41472
	ds_write_b128 v158, v[40:43] offset:50176
	ds_write_b128 v228, v[246:249] offset:32768
	ds_write_b128 v228, v[220:223] offset:41472
	ds_write_b128 v228, v[224:227] offset:50176
	s_and_saveexec_b64 s[14:15], s[2:3]
	ds_write_b128 v229, v[8:11] offset:58880
	s_or_b64 exec, exec, s[14:15]
	s_waitcnt lgkmcnt(0)
	s_barrier
	s_andn2_b64 vcc, exec, s[56:57]
	s_cbranch_vccnz .Lscanh_nopfb
	s_lshl_b32 s14, s76, 5
	s_addk_i32 s14, 0x60
	s_and_b64 vcc, exec, s[12:13]
	v_add_u32_e32 v0, s14, v113
	s_cbranch_vccnz .Lscanh_ib
	v_add_u32_e32 v1, s74, v113
	v_add_u32_e32 v1, 0x60, v1
	v_cmp_lt_i32_e32 vcc, s47, v1
	s_and_saveexec_b64 s[14:15], vcc
	s_xor_b64 s[14:15], exec, s[14:15]
	v_add_u32_e32 v0, s38, v156
	v_add_u32_e32 v0, 0x9bf, v0
	s_andn2_saveexec_b64 s[14:15], s[14:15]
	v_sub_u32_e32 v0, 0xff, v0
	s_or_b64 exec, exec, s[14:15]
.Lscanh_ib:
	v_add_u32_e32 v195, s101, v0
	v_ashrrev_i32_e32 v1, 31, v0
	v_lshl_add_u64 v[0:1], s[50:51], 0, v[0:1]
	v_lshlrev_b64 v[28:29], 12, v[0:1]
	v_lshlrev_b64 v[0:1], 11, v[0:1]
	v_lshl_add_u64 v[30:31], v[128:129], 0, v[0:1]
	v_lshl_add_u64 v[40:41], v[142:143], 0, v[28:29]
	v_lshl_add_u64 v[0:1], v[130:131], 0, v[0:1]
	global_load_dwordx4 v[28:31], v[30:31], off
	s_nop 0
	global_load_dwordx4 v[32:35], v[40:41], off
	global_load_dwordx4 v[36:39], v[0:1], off
	s_nop 0
	global_load_dwordx4 v[40:43], v[40:41], off offset:2048
	v_mov_b32_e32 v0, v195
	v_ashrrev_i32_e32 v1, 31, v0
	v_lshl_add_u64 v[0:1], s[50:51], 0, v[0:1]
	v_lshlrev_b64 v[212:213], 12, v[0:1]
	v_lshlrev_b64 v[0:1], 11, v[0:1]
	v_lshl_add_u64 v[214:215], v[128:129], 0, v[0:1]
	v_lshl_add_u64 v[224:225], v[142:143], 0, v[212:213]
	v_lshl_add_u64 v[0:1], v[130:131], 0, v[0:1]
	global_load_dwordx4 v[212:215], v[214:215], off
	s_nop 0
	global_load_dwordx4 v[216:219], v[224:225], off
	global_load_dwordx4 v[220:223], v[0:1], off
	s_nop 0
	global_load_dwordx4 v[224:227], v[224:225], off offset:2048
	s_and_saveexec_b64 s[14:15], s[2:3]
	s_cbranch_execz .Lscanh_eb
	global_load_dwordx4 v[8:11], v[250:251], off

; DI void hgrn_scan_mfma(const Params& p, char* shm) {
;     ...
;         for (int ch2 = 0; ch2 < LT / C; ch2 += 2) {
; #pragma unroll
;           for (int hh = 0; hh < 2; ++hh) {
;             const int ch = ch2 + hh;
;             if (hh == 0) HG_STAGE(ch, ra0, ra1, ra2, ra3, ra4); else HG_STAGE(ch, rb0, rb1, rb2, rb3, rb4);
.Lscanh_nopfb:
	s_sub_i32 s38, s38, 64
	s_add_i32 s74, s74, 64
	s_and_b64 vcc, exec, s[54:55]
	s_cbranch_vccnz .LBB0_2411
	s_mov_b32 s76, s75
	s_branch .Lscanh_loop
